# prologue de-serialisation: attn-B unit key-norm load issued with the Q loads (on top of loop-edge edits)
# speedup vs baseline: 1.0002x; 1.0002x over previous
.LBB0_663:
	s_or_b64 exec, exec, s[10:11]
	v_mov_b32_e32 v2, s93
	s_waitcnt lgkmcnt(0)
	s_barrier
	ds_read_b32 v2, v2
	s_mov_b64 s[12:13], -1
	s_waitcnt lgkmcnt(0)
	s_barrier
	v_readfirstlane_b32 s3, v2
	s_add_i32 s10, s3, s46
	s_cmp_ge_i32 s10, s47
	s_cbranch_scc1 .LBB0_658
	s_ashr_i32 s11, s10, 31
	s_lshl_b64 s[10:11], s[10:11], 1
	s_getpc_b64 s[12:13]
	s_add_u32 s12, s12, _ZL7B_UNITS@rel32@lo+4
	s_addc_u32 s13, s13, _ZL7B_UNITS@rel32@hi+12
	s_add_u32 s10, s12, s10
	s_addc_u32 s11, s13, s11
	global_load_ushort v2, v3, s[10:11]
	s_movk_i32 s3, 0x7000
	s_mov_b64 s[10:11], -1
	s_waitcnt vmcnt(0)
	v_cmp_gt_u32_e32 vcc, s3, v2
	v_readfirstlane_b32 s96, v2
	s_cbranch_vccz .LBB0_723
	s_and_b32 s3, s96, 0x7000
	s_bfe_u32 s33, s96, 0x30008
	s_addk_i32 s3, 0x1000
	s_cmpk_lt_u32 s96, 0x1000
	s_cselect_b64 s[22:23], -1, 0
	s_and_b64 s[10:11], s[22:23], exec
	s_cselect_b32 s31, 0, s3
	s_lshl_b32 s3, s96, 7
	s_and_b32 s40, s3, 0x7f80
	s_lshr_b32 s3, s96, 6
	s_and_b32 s3, s3, 0x1c0
	s_add_u32 s3, s72, s3
	s_addc_u32 s10, s73, 0
	s_lshl_b32 s11, s33, 3
	v_mov_b32_e32 v36, v0
	s_add_u32 s28, s3, s11
	s_addc_u32 s29, s10, 0
	v_readfirstlane_b32 s77, v36
	s_ashr_i32 s41, s77, 6
	s_and_b32 s3, s41, 3
	s_lshl_b32 s11, s3, 5
	s_ashr_i32 s10, s77, 8
	s_or_b32 s37, s11, s40
	s_mul_i32 s11, s33, 0x600000
	v_and_b32_e32 v160, 31, v36
	s_add_u32 s18, s70, s11
	v_or_b32_e32 v4, s37, v160
	s_addc_u32 s19, s71, 0
	s_lshl_b32 s12, s10, 6
	v_add_lshl_u32 v2, v4, s31, 8
	s_ashr_i32 s13, s12, 31
	v_bfe_u32 v161, v36, 5, 1
	v_lshl_add_u64 v[6:7], s[18:19], 0, v[2:3]
	s_lshl_b64 s[16:17], s[12:13], 1
	v_lshl_add_u64 v[6:7], v[6:7], 0, s[16:17]
	v_lshlrev_b32_e32 v138, 4, v161
	v_mov_b32_e32 v139, v3
	v_lshl_add_u64 v[6:7], v[6:7], 0, v[138:139]
	s_mov_b64 s[26:27], 0x9000000
	s_mov_b32 s11, 0x9000000
	v_lshl_add_u64 v[8:9], v[6:7], 0, s[26:27]
	v_add_co_u32_e32 v6, vcc, s11, v6
	s_add_u32 s26, s18, 0xc000000
	s_nop 0
	v_addc_co_u32_e32 v7, vcc, 0, v7, vcc
	s_addc_u32 s27, s19, 0
	global_load_dwordx4 v[102:105], v[6:7], off
	global_load_dwordx4 v[106:109], v[8:9], off offset:32
	global_load_dwordx4 v[110:113], v[8:9], off offset:64
	global_load_dwordx4 v[114:117], v[8:9], off offset:96
	v_lshl_add_u64 v[6:7], s[26:27], 0, v[2:3]
	v_lshl_add_u64 v[6:7], v[6:7], 0, s[16:17]
	v_lshl_add_u64 v[18:19], v[6:7], 0, v[138:139]
	global_load_dwordx4 v[6:9], v[18:19], off offset:96
	global_load_dwordx4 v[10:13], v[18:19], off offset:64
	global_load_dwordx4 v[14:17], v[18:19], off offset:32
	s_nop 0
	global_load_dwordx4 v[18:21], v[18:19], off
	s_lshl_b32 s100, s10, 2
	s_add_u32 s100, s28, s100
	s_addc_u32 s101, s29, 0
	global_load_dword v186, v3, s[100:101]
	s_add_i32 s11, s33, 1
	v_cvt_f32_ubyte0_e32 v5, s11
	v_exp_f32_e64 v5, -v5
	v_and_b32_e32 v159, 63, v36
	s_waitcnt vmcnt(0)
	v_readfirstlane_b32 s11, v5
	v_lshlrev_b32_e32 v2, 16, v102
	v_lshlrev_b32_e32 v5, 16, v18
	v_fma_f32 v22, v2, v2, 0
	v_fma_f32 v2, v2, v5, 0
	v_and_b32_e32 v5, 0xffff0000, v102
	v_and_b32_e32 v18, 0xffff0000, v18
	v_fmac_f32_e32 v22, v5, v5
	v_fmac_f32_e32 v2, v5, v18
	v_lshlrev_b32_e32 v5, 16, v103
	v_lshlrev_b32_e32 v18, 16, v19
	v_fmac_f32_e32 v22, v5, v5
	v_fmac_f32_e32 v2, v5, v18
	v_and_b32_e32 v5, 0xffff0000, v103
	v_and_b32_e32 v18, 0xffff0000, v19
	v_fmac_f32_e32 v22, v5, v5
	v_fmac_f32_e32 v2, v5, v18
	v_lshlrev_b32_e32 v5, 16, v104
	v_lshlrev_b32_e32 v18, 16, v20
	v_fmac_f32_e32 v22, v5, v5
	v_fmac_f32_e32 v2, v5, v18
	v_and_b32_e32 v5, 0xffff0000, v104
	v_and_b32_e32 v18, 0xffff0000, v20
	v_fmac_f32_e32 v22, v5, v5
	v_fmac_f32_e32 v2, v5, v18
	v_lshlrev_b32_e32 v5, 16, v105
	v_lshlrev_b32_e32 v18, 16, v21
	v_fmac_f32_e32 v22, v5, v5
	v_fmac_f32_e32 v2, v5, v18
	v_and_b32_e32 v5, 0xffff0000, v105
	v_and_b32_e32 v18, 0xffff0000, v21
	v_fmac_f32_e32 v22, v5, v5
	v_fmac_f32_e32 v2, v5, v18
	v_lshlrev_b32_e32 v5, 16, v106
	v_lshlrev_b32_e32 v18, 16, v14
	v_fmac_f32_e32 v22, v5, v5
	v_fmac_f32_e32 v2, v5, v18
	v_and_b32_e32 v5, 0xffff0000, v106
	v_and_b32_e32 v14, 0xffff0000, v14
	v_fmac_f32_e32 v22, v5, v5
	v_fmac_f32_e32 v2, v5, v14
	v_lshlrev_b32_e32 v5, 16, v107
	v_lshlrev_b32_e32 v14, 16, v15
	v_fmac_f32_e32 v22, v5, v5
	v_fmac_f32_e32 v2, v5, v14
	v_and_b32_e32 v5, 0xffff0000, v107
	v_and_b32_e32 v14, 0xffff0000, v15
	v_fmac_f32_e32 v22, v5, v5
	v_fmac_f32_e32 v2, v5, v14
	v_lshlrev_b32_e32 v5, 16, v108
	v_lshlrev_b32_e32 v14, 16, v16
	v_fmac_f32_e32 v22, v5, v5
	v_fmac_f32_e32 v2, v5, v14
	v_and_b32_e32 v5, 0xffff0000, v108
	v_and_b32_e32 v14, 0xffff0000, v16
	v_fmac_f32_e32 v22, v5, v5
	v_fmac_f32_e32 v2, v5, v14
	v_lshlrev_b32_e32 v5, 16, v109
	v_lshlrev_b32_e32 v14, 16, v17
	v_fmac_f32_e32 v22, v5, v5
	v_fmac_f32_e32 v2, v5, v14
	v_and_b32_e32 v5, 0xffff0000, v109
	v_and_b32_e32 v14, 0xffff0000, v17
	v_fmac_f32_e32 v22, v5, v5
	v_fmac_f32_e32 v2, v5, v14
	v_lshlrev_b32_e32 v5, 16, v110
	v_lshlrev_b32_e32 v14, 16, v10
	v_fmac_f32_e32 v22, v5, v5
	v_fmac_f32_e32 v2, v5, v14
	v_and_b32_e32 v5, 0xffff0000, v110
	v_and_b32_e32 v10, 0xffff0000, v10
	v_fmac_f32_e32 v22, v5, v5
	v_fmac_f32_e32 v2, v5, v10
	v_lshlrev_b32_e32 v5, 16, v111
	v_lshlrev_b32_e32 v10, 16, v11
	v_fmac_f32_e32 v22, v5, v5
	v_fmac_f32_e32 v2, v5, v10
	v_and_b32_e32 v5, 0xffff0000, v111
	v_and_b32_e32 v10, 0xffff0000, v11
	v_fmac_f32_e32 v22, v5, v5
	v_fmac_f32_e32 v2, v5, v10
	v_lshlrev_b32_e32 v5, 16, v112
	v_lshlrev_b32_e32 v10, 16, v12
	v_fmac_f32_e32 v22, v5, v5
	v_fmac_f32_e32 v2, v5, v10
	v_and_b32_e32 v5, 0xffff0000, v112
	v_and_b32_e32 v10, 0xffff0000, v12
	v_fmac_f32_e32 v22, v5, v5
	v_fmac_f32_e32 v2, v5, v10
	v_lshlrev_b32_e32 v5, 16, v113
	v_lshlrev_b32_e32 v10, 16, v13
	v_fmac_f32_e32 v22, v5, v5
	v_fmac_f32_e32 v2, v5, v10
	v_and_b32_e32 v5, 0xffff0000, v113
	v_and_b32_e32 v10, 0xffff0000, v13
	v_fmac_f32_e32 v22, v5, v5
	v_fmac_f32_e32 v2, v5, v10
	v_lshlrev_b32_e32 v5, 16, v114
	v_lshlrev_b32_e32 v10, 16, v6
	v_fmac_f32_e32 v22, v5, v5
	v_fmac_f32_e32 v2, v5, v10
	v_and_b32_e32 v5, 0xffff0000, v114
	v_and_b32_e32 v6, 0xffff0000, v6
	v_fmac_f32_e32 v22, v5, v5
	v_fmac_f32_e32 v2, v5, v6
	v_lshlrev_b32_e32 v5, 16, v115
	v_lshlrev_b32_e32 v6, 16, v7
	v_fmac_f32_e32 v22, v5, v5
	v_fmac_f32_e32 v2, v5, v6
	v_and_b32_e32 v5, 0xffff0000, v115
	v_and_b32_e32 v6, 0xffff0000, v7
	v_fmac_f32_e32 v22, v5, v5
	v_fmac_f32_e32 v2, v5, v6
	v_lshlrev_b32_e32 v5, 16, v116
	v_lshlrev_b32_e32 v6, 16, v8
	v_fmac_f32_e32 v22, v5, v5
	v_fmac_f32_e32 v2, v5, v6
	v_and_b32_e32 v5, 0xffff0000, v116
	v_and_b32_e32 v6, 0xffff0000, v8
	v_fmac_f32_e32 v22, v5, v5
	v_fmac_f32_e32 v2, v5, v6
	v_lshlrev_b32_e32 v5, 16, v117
	v_lshlrev_b32_e32 v6, 16, v9
	v_fmac_f32_e32 v22, v5, v5
	v_fmac_f32_e32 v2, v5, v6
	v_and_b32_e32 v5, 0xffff0000, v117
	v_and_b32_e32 v6, 0xffff0000, v9
	v_fmac_f32_e32 v2, v5, v6
	ds_bpermute_b32 v6, v157, v2
	v_mul_f32_e32 v162, s11, v249
	s_waitcnt lgkmcnt(0)
	v_add_f32_e32 v2, v2, v6
	v_fmac_f32_e32 v22, v5, v5
	ds_bpermute_b32 v5, v157, v22
	v_mul_f32_e32 v2, 0x3e38aa3b, v2
	s_mov_b32 s11, 0x3f8020c5
	s_waitcnt lgkmcnt(0)
	v_add_f32_e32 v5, v22, v5
	s_waitcnt vmcnt(0)
	v_mul_f32_e32 v5, v186, v5
	v_cmp_gt_f32_e32 vcc, s2, v5
	v_mul_f32_e32 v6, 0x4f800000, v5
	s_nop 0
	v_cndmask_b32_e32 v5, v5, v6, vcc
	v_sqrt_f32_e32 v6, v5
	s_nop 0
	v_add_u32_e32 v7, -1, v6
	v_fma_f32 v8, -v7, v6, v5
	v_cmp_ge_f32_e64 s[38:39], 0, v8
	v_add_u32_e32 v8, 1, v6
	s_nop 0
	v_cndmask_b32_e64 v7, v6, v7, s[38:39]
	v_fma_f32 v6, -v8, v6, v5
	v_cmp_lt_f32_e64 s[38:39], 0, v6
	s_nop 1
	v_cndmask_b32_e64 v6, v7, v8, s[38:39]
	v_mul_f32_e32 v7, 0x37800000, v6
	v_cndmask_b32_e32 v6, v6, v7, vcc
	v_cmp_class_f32_e32 vcc, v5, v231
	s_nop 1
	v_cndmask_b32_e32 v5, v6, v5, vcc
	v_mul_f32_e32 v5, 0x3e38aa3b, v5
	v_fma_f32 v2, v5, s11, -v2
	v_add_f32_e32 v2, 0x42200000, v2
	v_div_scale_f32 v5, s[16:17], -v162, -v162, v2
	v_rcp_f32_e32 v6, v5
	s_nop 0
	v_fma_f32 v7, -v5, v6, 1.0
	v_fmac_f32_e32 v6, v7, v6
	v_div_scale_f32 v7, vcc, v2, -v162, v2
	v_mul_f32_e32 v8, v7, v6
	v_fma_f32 v9, -v5, v8, v7
	v_fmac_f32_e32 v8, v9, v6
	v_fma_f32 v5, -v5, v8, v7
	v_div_fmas_f32 v5, v5, v6, v8
	v_div_fixup_f32 v2, v5, -v162, v2
	ds_bpermute_b32 v5, v152, v2
	v_cmp_eq_u32_e32 vcc, 0, v159
	s_waitcnt lgkmcnt(0)
	v_max_f32_e32 v5, v5, v5
	v_max_f32_e32 v2, v2, v5
	ds_bpermute_b32 v5, v153, v2
	s_waitcnt lgkmcnt(0)
	v_max_f32_e32 v5, v5, v5
	v_max_f32_e32 v2, v2, v5
	ds_bpermute_b32 v5, v154, v2
	s_waitcnt lgkmcnt(0)
	v_max_f32_e32 v5, v5, v5
	v_max_f32_e32 v2, v2, v5
	ds_bpermute_b32 v5, v155, v2
	s_waitcnt lgkmcnt(0)
	v_max_f32_e32 v5, v5, v5
	v_max_f32_e32 v2, v2, v5
	ds_bpermute_b32 v5, v156, v2
	s_and_saveexec_b64 s[28:29], vcc
	s_cbranch_execz .LBB0_667
	s_lshl_b32 s11, s41, 2
	s_add_i32 s11, s11, 0
	s_waitcnt lgkmcnt(0)
	v_max_f32_e32 v5, v5, v5
	v_max_f32_e32 v2, v2, v2
	s_add_i32 s11, s11, 0x21800
	v_max_f32_e32 v2, v2, v5
	v_mov_b32_e32 v5, s11
	ds_write_b32 v5, v2
